# adds: diff-attn loop bookkeeping SALU moved into MFMA shadows, loop back-edge rotated, o rescale done inside the rare path (no per-tile flag test)
# speedup vs baseline: 1.0825x; 1.0022x over previous
; #define MFMA32(a, b, c) __builtin_amdgcn_mfma_f32_32x32x16_bf16((a), (b), (c), 0, 0, 0)
; #define VLOAD(dst, sbv, q) do { _Pragma("unroll") for (int d_ = 0; d_ < 4; ++d_) dst[d_] = *(const lds_bf16x8*)((sbv) + vo[q] + d_ * 4096); } while (0)
; #define FENCE __builtin_amdgcn_sched_barrier(0)
; DI void diff_unit(KP p, int l, int b, int h, int qb, int isctx, float lamv, float lam_init, char* ldsc) {
;     ...
;   for (int kt = 0; kt < nt - 1; ++kt) {
;     asm volatile("s_waitcnt vmcnt(0)" ::: "memory");
;     __builtin_amdgcn_s_barrier();
;     const int stg1 = stg == 2 ? 0 : stg + 1;
;     if (kt + 2 < nt) { const int s2_ = stg >= 1 ? stg - 1 : 2; DISSUE(kt + 2, s2_); }
;     if (need) {
; #pragma unroll
;       for (int d = 0; d < 4; ++d) o[d] *= alpha;
;     }
;     const lds_u8* sbv = L + stg * STG + 16384;
;     const lds_u8* sbk = L + stg1 * STG + comp * 8192;
;     bf16x8 kf[2][4];
;     f32x16 st[2];
; #pragma unroll
;     for (int t = 0; t < 2; ++t)
; #pragma unroll
;       for (int ks = 0; ks < 4; ++ks) kf[t][ks] = *(const lds_bf16x8*)(sbk + ko[ks] + t * 4096);
;     FENCE;
;     pv_grp(o, vA, P[0]); pv_grp(o, vB, P[1]);
;     VLOAD(vA, sbv, 2); VLOAD(vB, sbv, 3);
;     FENCE;
; #pragma unroll
;     for (int i = 0; i < 16; ++i) { st[0][i] = 0.f; st[1][i] = 0.f; }
; #pragma unroll
;     for (int ks = 0; ks < 4; ++ks) st[0] = MFMA32(kf[0][ks], qf[ks], st[0]);
; #pragma unroll
;     for (int ks = 0; ks < 4; ++ks) st[1] = MFMA32(kf[1][ks], qf[ks], st[1]);
;     FENCE;
;     pv_grp(o, vA, P[2]);
;     const float mx = tile_max(st);
;     need = !__all(mx <= m + 8.0f);
;     const float mn = need ? fmaxf(m, mx) : m;
;     alpha = __builtin_amdgcn_exp2f(m - mn);
;     FENCE;
;     float ps = exp_pack1<0>(st, mn, P[0]);
;     ps += exp_pack1<1>(st, mn, P[1]);
;     ps += exp_pack1<2>(st, mn, P[2]);
;     pv_grp(o, vB, P[3]);
;     ps += exp_pack1<3>(st, mn, P[3]);
; #pragma unroll
;     for (int q = 0; q < 4; ++q) { __builtin_amdgcn_sched_group_barrier(0x402, 18, 0); __builtin_amdgcn_sched_group_barrier(0x008, 1, 0); }
;     lsum = lsum * alpha + ps; m = mn;
;     FENCE;
;     { const lds_u8* sbn = L + stg1 * STG + 16384; VLOAD(vA, sbn, 0); VLOAD(vB, sbn, 1); }
;     stg = stg1;
;   }
.LBB0_475:
.LBB0_477:
	ds_read_b128 v[154:157], v136
	ds_read_b128 v[192:195], v136 offset:4096
	ds_read_b128 v[196:199], v137
	ds_read_b128 v[200:203], v137 offset:4096
	ds_read_b128 v[204:207], v138
	ds_read_b128 v[208:211], v138 offset:4096
	ds_read_b128 v[212:215], v139
	ds_read_b128 v[216:219], v139 offset:4096
	s_waitcnt lgkmcnt(8)
	v_mfma_f32_32x32x16_bf16 v[50:65], v[86:89], v[66:69], v[50:65]
	s_add_i32 s2, s17, 1
	s_and_b32 s16, s2, 3
	s_lshl_b32 s15, s16, 15
	ds_read_b128 v[220:223], v248 offset:24576
	ds_read_b128 v[224:227], v248 offset:28672
	s_add_i32 s18, s3, 0xc0
	s_add_i32 s19, s10, 64
	s_cmp_eq_u32 s11, 0
	s_cselect_b32 s19, s18, s19
	s_add_i32 s11, s11, 1
	s_add_i32 s10, s10, 64
	s_mul_i32 s19, s19, 0x1600
	s_add_u32 s18, s22, s19
	s_addc_u32 s19, s23, 0
	s_add_i32 s24, s17, 3
	s_and_b32 s24, s24, 3
	s_lshl_b32 s24, s24, 15
	s_add_i32 s24, s13, s24
	s_mov_b32 m0, s24
	v_mfma_f32_32x32x16_bf16 v[34:49], v[82:85], v[66:69], v[34:49]
	global_load_lds_dwordx4 v244, s[18:19]
	s_add_i32 m0, s24, 0x2000
	v_mfma_f32_32x32x16_bf16 v[18:33], v[78:81], v[66:69], v[18:33]
	v_mfma_f32_32x32x16_bf16 v[2:17], v[74:77], v[66:69], v[2:17]
	v_mov_b64_e32 v[66:67], v[252:253]
	v_mov_b64_e32 v[68:69], v[252:253]
	v_mov_b64_e32 v[74:75], v[252:253]
	global_load_lds_dwordx4 v245, s[18:19]
	s_add_i32 s18, s16, 1
	s_and_b32 s18, s18, 3
	s_lshl_b32 s18, s18, 15
	s_add_i32 s18, s18, s14
	s_add_i32 m0, s24, 0x4000
	v_mfma_f32_32x32x16_bf16 v[50:65], v[126:129], v[70:73], v[50:65]
	v_mov_b64_e32 v[76:77], v[252:253]
	v_mov_b64_e32 v[78:79], v[252:253]
	v_mov_b64_e32 v[80:81], v[252:253]
	ds_read_b128 v[126:129], v248 offset:20480
	v_mfma_f32_32x32x16_bf16 v[34:49], v[122:125], v[70:73], v[34:49]
	ds_read_b128 v[122:125], v248 offset:16384
	ds_read_b128 v[228:231], v255 offset:16384
	ds_read_b128 v[232:235], v255 offset:20480
	ds_read_b128 v[236:239], v255 offset:24576
	ds_read_b128 v[240:243], v255 offset:28672
	v_mfma_f32_32x32x16_bf16 v[18:33], v[94:97], v[70:73], v[18:33]
	v_mfma_f32_32x32x16_bf16 v[2:17], v[90:93], v[70:73], v[2:17]
	v_mov_b64_e32 v[70:71], v[252:253]
	v_mov_b64_e32 v[72:73], v[252:253]
	global_load_lds_dwordx4 v246, s[20:21]
	s_add_i32 m0, s24, 0x6000
	s_waitcnt lgkmcnt(8)
	v_mfma_f32_32x32x16_bf16 v[82:97], v[154:157], v[98:101], v[66:81]
	v_mfma_f32_32x32x16_bf16 v[66:81], v[192:195], v[98:101], v[66:81]
	v_mfma_f32_32x32x16_bf16 v[66:81], v[200:203], v[102:105], v[66:81]
	v_mfma_f32_32x32x16_bf16 v[82:97], v[196:199], v[102:105], v[82:97]
	global_load_lds_dwordx4 v247, s[20:21]
	s_add_u32 s20, s20, 0x80
	s_addc_u32 s21, s21, 0
	v_mfma_f32_32x32x16_bf16 v[66:81], v[208:211], v[106:109], v[66:81]
	v_mfma_f32_32x32x16_bf16 v[82:97], v[204:207], v[106:109], v[82:97]
	v_mfma_f32_32x32x16_bf16 v[66:81], v[216:219], v[110:113], v[66:81]
	v_mfma_f32_32x32x16_bf16 v[82:97], v[212:215], v[110:113], v[82:97]
	s_waitcnt lgkmcnt(0)
	v_mfma_f32_32x32x16_bf16 v[50:65], v[122:125], v[118:121], v[50:65]
	v_add_u32_e32 v251, s15, v150
	v_add_u32_e32 v249, s15, v151
	v_add_u32_e32 v136, s18, v141
	v_add_u32_e32 v137, s18, v145
	v_add_u32_e32 v138, s18, v147
	v_add_u32_e32 v139, s18, v148
	s_mov_b32 s17, s16
	s_cmpk_lg_i32 s11, 0x83
	v_add_u32_e32 v248, s15, v149
	v_add_u32_e32 v255, s15, v146
	v_mfma_f32_32x32x16_bf16 v[34:49], v[126:129], v[118:121], v[34:49]
	v_exp_f32_e32 v122, v82
	v_exp_f32_e32 v124, v83
	v_exp_f32_e32 v126, v84
	v_exp_f32_e32 v128, v85
	v_exp_f32_e32 v156, v86
	v_mfma_f32_32x32x16_bf16 v[18:33], v[220:223], v[118:121], v[18:33]
	v_exp_f32_e32 v192, v87
	v_exp_f32_e32 v194, v88
	v_exp_f32_e32 v196, v89
	v_exp_f32_e32 v123, v90
	v_exp_f32_e32 v125, v91
	v_mfma_f32_32x32x16_bf16 v[2:17], v[224:227], v[118:121], v[2:17]
	v_exp_f32_e32 v127, v92
	v_exp_f32_e32 v129, v93
	v_exp_f32_e32 v157, v94
	v_exp_f32_e32 v193, v95
	v_exp_f32_e32 v195, v96
	v_mfma_f32_32x32x16_bf16 v[50:65], v[228:231], v[114:117], v[50:65]
	v_exp_f32_e32 v197, v97
	v_exp_f32_e32 v83, v66
	v_exp_f32_e32 v67, v67
	v_exp_f32_e32 v85, v68
	v_exp_f32_e32 v69, v69
	v_mfma_f32_32x32x16_bf16 v[34:49], v[232:235], v[114:117], v[34:49]
	v_exp_f32_e32 v87, v70
	v_exp_f32_e32 v71, v71
	v_exp_f32_e32 v89, v72
	v_exp_f32_e32 v73, v73
	v_pk_add_f32 v[92:93], v[124:125], v[122:123]
	v_pk_add_f32 v[92:93], v[126:127], v[92:93]
	v_mfma_f32_32x32x16_bf16 v[18:33], v[236:239], v[114:117], v[18:33]
	v_exp_f32_e32 v82, v74
	v_exp_f32_e32 v66, v75
	v_exp_f32_e32 v84, v76
	v_exp_f32_e32 v68, v77
	v_pk_add_f32 v[92:93], v[128:129], v[92:93]
	v_pk_add_f32 v[92:93], v[156:157], v[92:93]
	v_mfma_f32_32x32x16_bf16 v[2:17], v[240:243], v[114:117], v[2:17]
	v_exp_f32_e32 v86, v78
	v_exp_f32_e32 v70, v79
	v_exp_f32_e32 v88, v80
	v_exp_f32_e32 v72, v81
	v_pk_add_f32 v[92:93], v[192:193], v[92:93]
	v_pk_add_f32 v[92:93], v[194:195], v[92:93]
	v_pk_add_f32 v[92:93], v[196:197], v[92:93]
	ds_read_b128 v[78:81], v251 offset:24576
	ds_read_b128 v[74:77], v251 offset:28672
	v_pk_add_f32 v[198:199], v[66:67], v[82:83]
	v_pk_add_f32 v[198:199], v[84:85], v[198:199]
	v_pk_add_f32 v[198:199], v[68:69], v[198:199]
	v_pk_add_f32 v[198:199], v[86:87], v[198:199]
	v_pk_add_f32 v[198:199], v[70:71], v[198:199]
	v_pk_add_f32 v[198:199], v[88:89], v[198:199]
	v_pk_add_f32 v[198:199], v[72:73], v[198:199]
	v_pk_add_f32 v[198:199], v[198:199], v[92:93]
	v_max_f32_e32 v200, v198, v199
	v_cmp_lt_f32_e32 vcc, 0x43000000, v200
	s_cbranch_vccnz .Ldiff_rare
; #define VLOAD(dst, sbv, q) do { _Pragma("unroll") for (int d_ = 0; d_ < 4; ++d_) dst[d_] = *(const lds_bf16x8*)((sbv) + vo[q] + d_ * 4096); } while (0)
; #define FENCE __builtin_amdgcn_sched_barrier(0)
; DI void diff_unit(KP p, int l, int b, int h, int qb, int isctx, float lamv, float lam_init, char* ldsc) {
;     ...
;     pv_grp(o, vA, P[2]);
;     const float mx = tile_max(st);
;     need = !__all(mx <= m + 8.0f);
;     const float mn = need ? fmaxf(m, mx) : m;
;     alpha = __builtin_amdgcn_exp2f(m - mn);
;     FENCE;
;     float ps = exp_pack1<0>(st, mn, P[0]);
;     ps += exp_pack1<1>(st, mn, P[1]);
;     ps += exp_pack1<2>(st, mn, P[2]);
;     pv_grp(o, vB, P[3]);
;     ps += exp_pack1<3>(st, mn, P[3]);
; #pragma unroll
;     for (int q = 0; q < 4; ++q) { __builtin_amdgcn_sched_group_barrier(0x402, 18, 0); __builtin_amdgcn_sched_group_barrier(0x008, 1, 0); }
;     lsum = lsum * alpha + ps; m = mn;
;     FENCE;
;     { const lds_u8* sbn = L + stg1 * STG + 16384; VLOAD(vA, sbn, 0); VLOAD(vB, sbn, 1); }
;     stg = stg1;
.Ldiff_rare_back:
	v_cvt_pk_bf16_f32 v118, v83, v67
	v_cvt_pk_bf16_f32 v114, v82, v66
	v_cvt_pk_bf16_f32 v119, v85, v69
	v_cvt_pk_bf16_f32 v120, v87, v71
	v_cvt_pk_bf16_f32 v121, v89, v73
	v_cvt_pk_bf16_f32 v115, v84, v68
	v_cvt_pk_bf16_f32 v116, v86, v70
	v_cvt_pk_bf16_f32 v117, v88, v72
	ds_read_b128 v[86:89], v251 offset:16384
	ds_read_b128 v[82:85], v251 offset:20480
	v_cvt_pk_bf16_f32 v66, v122, v124
	v_cvt_pk_bf16_f32 v67, v126, v128
	v_cvt_pk_bf16_f32 v70, v123, v125
	v_cvt_pk_bf16_f32 v71, v127, v129
	ds_read_b128 v[126:129], v249 offset:16384
	ds_read_b128 v[122:125], v249 offset:20480
	v_pk_add_f32 v[152:153], v[152:153], v[198:199]
	ds_read_b128 v[94:97], v249 offset:24576
	ds_read_b128 v[90:93], v249 offset:28672
	v_cvt_pk_bf16_f32 v68, v156, v192
	v_cvt_pk_bf16_f32 v69, v194, v196
	v_cvt_pk_bf16_f32 v72, v157, v193
	v_cvt_pk_bf16_f32 v73, v195, v197
	s_cbranch_scc1 .LBB0_471
	s_branch .LBB0_479
.Ldiff_rare:
	v_max3_f32 v201, v66, v67, v82
	v_max3_f32 v201, v201, v83, v84
	v_max3_f32 v201, v201, v85, v68
	v_max3_f32 v201, v201, v69, v86
	v_max3_f32 v201, v201, v87, v70
	v_max3_f32 v201, v201, v71, v88
	v_max3_f32 v201, v201, v89, v72
	v_max3_f32 v201, v201, v73, v122
	v_max3_f32 v201, v201, v123, v124
	v_max3_f32 v201, v201, v125, v126
	v_max3_f32 v201, v201, v127, v128
	v_max3_f32 v201, v201, v129, v156
	v_max3_f32 v201, v201, v157, v192
	v_max3_f32 v201, v201, v193, v194
	v_max3_f32 v201, v201, v195, v196
	v_max_f32_e32 v201, v201, v197
	v_mov_b32_e32 v202, v201
	s_nop 1
	v_permlane32_swap_b32_e32 v201, v202
	v_max_f32_e32 v201, v201, v202
	v_frexp_exp_i32_f32_e32 v202, v201
	v_max_i32_e32 v202, 0, v202
	v_sub_u32_e32 v203, 0, v202
	v_ldexp_f32 v140, 1.0, v203
	v_cvt_f32_i32_e32 v203, v202
	v_sub_f32_e32 v252, v252, v203
	v_mov_b32_e32 v253, v252
	v_pk_mul_f32 v[66:67], v[66:67], v[140:141] op_sel_hi:[1,0]
	v_pk_mul_f32 v[82:83], v[82:83], v[140:141] op_sel_hi:[1,0]
	v_pk_mul_f32 v[84:85], v[84:85], v[140:141] op_sel_hi:[1,0]
	v_pk_mul_f32 v[68:69], v[68:69], v[140:141] op_sel_hi:[1,0]
	v_pk_mul_f32 v[86:87], v[86:87], v[140:141] op_sel_hi:[1,0]
	v_pk_mul_f32 v[70:71], v[70:71], v[140:141] op_sel_hi:[1,0]
	v_pk_mul_f32 v[88:89], v[88:89], v[140:141] op_sel_hi:[1,0]
	v_pk_mul_f32 v[72:73], v[72:73], v[140:141] op_sel_hi:[1,0]
	v_pk_mul_f32 v[122:123], v[122:123], v[140:141] op_sel_hi:[1,0]
	v_pk_mul_f32 v[124:125], v[124:125], v[140:141] op_sel_hi:[1,0]
	v_pk_mul_f32 v[126:127], v[126:127], v[140:141] op_sel_hi:[1,0]
	v_pk_mul_f32 v[128:129], v[128:129], v[140:141] op_sel_hi:[1,0]
	v_pk_mul_f32 v[156:157], v[156:157], v[140:141] op_sel_hi:[1,0]
	v_pk_mul_f32 v[192:193], v[192:193], v[140:141] op_sel_hi:[1,0]
	v_pk_mul_f32 v[194:195], v[194:195], v[140:141] op_sel_hi:[1,0]
	v_pk_mul_f32 v[196:197], v[196:197], v[140:141] op_sel_hi:[1,0]
	v_pk_mul_f32 v[198:199], v[198:199], v[140:141] op_sel_hi:[1,0]
	v_pk_mul_f32 v[152:153], v[152:153], v[140:141] op_sel_hi:[1,0]
	v_pk_mul_f32 v[2:3], v[2:3], v[140:141] op_sel_hi:[1,0]
	v_pk_mul_f32 v[4:5], v[4:5], v[140:141] op_sel_hi:[1,0]
	v_pk_mul_f32 v[6:7], v[6:7], v[140:141] op_sel_hi:[1,0]
	v_pk_mul_f32 v[8:9], v[8:9], v[140:141] op_sel_hi:[1,0]
	v_pk_mul_f32 v[10:11], v[10:11], v[140:141] op_sel_hi:[1,0]
	v_pk_mul_f32 v[12:13], v[12:13], v[140:141] op_sel_hi:[1,0]
	v_pk_mul_f32 v[14:15], v[14:15], v[140:141] op_sel_hi:[1,0]
	v_pk_mul_f32 v[16:17], v[16:17], v[140:141] op_sel_hi:[1,0]
	v_pk_mul_f32 v[18:19], v[18:19], v[140:141] op_sel_hi:[1,0]
	v_pk_mul_f32 v[20:21], v[20:21], v[140:141] op_sel_hi:[1,0]
	v_pk_mul_f32 v[22:23], v[22:23], v[140:141] op_sel_hi:[1,0]
	v_pk_mul_f32 v[24:25], v[24:25], v[140:141] op_sel_hi:[1,0]
	v_pk_mul_f32 v[26:27], v[26:27], v[140:141] op_sel_hi:[1,0]
	v_pk_mul_f32 v[28:29], v[28:29], v[140:141] op_sel_hi:[1,0]
	v_pk_mul_f32 v[30:31], v[30:31], v[140:141] op_sel_hi:[1,0]
	v_pk_mul_f32 v[32:33], v[32:33], v[140:141] op_sel_hi:[1,0]
	v_pk_mul_f32 v[34:35], v[34:35], v[140:141] op_sel_hi:[1,0]
	v_pk_mul_f32 v[36:37], v[36:37], v[140:141] op_sel_hi:[1,0]
	v_pk_mul_f32 v[38:39], v[38:39], v[140:141] op_sel_hi:[1,0]
	v_pk_mul_f32 v[40:41], v[40:41], v[140:141] op_sel_hi:[1,0]
	v_pk_mul_f32 v[42:43], v[42:43], v[140:141] op_sel_hi:[1,0]
	v_pk_mul_f32 v[44:45], v[44:45], v[140:141] op_sel_hi:[1,0]
	v_pk_mul_f32 v[46:47], v[46:47], v[140:141] op_sel_hi:[1,0]
	v_pk_mul_f32 v[48:49], v[48:49], v[140:141] op_sel_hi:[1,0]
	v_pk_mul_f32 v[50:51], v[50:51], v[140:141] op_sel_hi:[1,0]
	v_pk_mul_f32 v[52:53], v[52:53], v[140:141] op_sel_hi:[1,0]
	v_pk_mul_f32 v[54:55], v[54:55], v[140:141] op_sel_hi:[1,0]
	v_pk_mul_f32 v[56:57], v[56:57], v[140:141] op_sel_hi:[1,0]
	v_pk_mul_f32 v[58:59], v[58:59], v[140:141] op_sel_hi:[1,0]
	v_pk_mul_f32 v[60:61], v[60:61], v[140:141] op_sel_hi:[1,0]
	v_pk_mul_f32 v[62:63], v[62:63], v[140:141] op_sel_hi:[1,0]
	v_pk_mul_f32 v[64:65], v[64:65], v[140:141] op_sel_hi:[1,0]
	s_branch .Ldiff_rare_back
